# v79 plus grid-size guards (permutations only when gridDim==256) for robustness
# baseline (speedup 1.0000x reference)
; #define LAS __attribute__((address_space(3)))
; DI float silu_f(float x) { return x / (1.0f + __expf(-x)); }
; DI void tok0_mix_dil(ldsp lds, const Params& p, const float* P, float* BRo, int task, int tid, int wid, int lane) {
;     const int b = task >> 2, hm = task & 3;
;     const float* pr = P + (size_t)b * 8192;
;     LAS float* OUT = (LAS float*)(lds + 65536); LAS float* S18 = OUT + 64;
;     tok0_mem(lds, pr + DB_QM + hm * 64, p.mem + (size_t)b * 256 * 1024, p.mem_norm_w, p.w_memkv + (size_t)1024 * 512, hm, OUT, tid, wid, lane);
;     if (tid < 64) BRo[(size_t)b * 1024 + 768 + hm * 64 + tid] = OUT[tid] * silu_f(pr[DB_GATE + 768 + hm * 64 + tid]);
;     if (hm == 0) {
;         for (int pi = wid; pi < 18; pi += 8) {
;             const int g = pi / 6, head = pi - g * 6;
;             const float* qp = pr + g * 2304 + head * 128; const float* kp = qp + 768;
;             const float t = wave_sum(qp[lane] * kp[lane] + qp[64 + lane] * kp[64 + lane]) * 0.08838834764831845f;
;             if (lane == 0) S18[pi] = t;
;         }
;         __syncthreads();
;         for (int c = tid; c < 768; c += 512) {
; __global__ void __launch_bounds__(NTHREADS, 2) megak(Params p) {
;     ...
;                 for (int t = blockIdx.x; t < BATCH * 4; t += gridDim.x) tok0_mix_dil(lds, p, T0P, T0BR, t, tid, wid, lane);
.LBB0_91:
	s_andn2_b64 vcc, exec, s[40:41]
	s_cbranch_vccnz .LBB0_126
	v_readlane_b32 s14, v251, 45
	v_readlane_b32 s15, v251, 46
	s_andn2_b64 vcc, exec, s[14:15]
	s_waitcnt vmcnt(0) lgkmcnt(0)
	s_barrier
	s_cbranch_vccnz .LBB0_126
	v_mov_b32_e32 v33, v12
	v_mov_b64_e32 v[30:31], v[32:33]
	v_ashrrev_i32_e32 v33, 31, v32
	v_lshlrev_b64 v[0:1], 11, v[32:33]
	s_mov_b64 s[14:15], 0x100000
	v_lshl_add_u64 v[78:79], v[0:1], 0, s[14:15]
	v_and_b32_e32 v0, 64, v233
	v_add_u32_e32 v0, 64, v0
	v_xor_b32_e32 v1, 32, v233
	v_cmp_lt_i32_e32 vcc, v1, v0
	s_lshl_b32 s22, s16, 5
	v_readlane_b32 s0, v255, 14
	v_cndmask_b32_e32 v1, v233, v1, vcc
	v_lshlrev_b32_e32 v95, 2, v1
	v_xor_b32_e32 v1, 16, v233
	v_cmp_lt_i32_e32 vcc, v1, v0
	s_cmp_lt_u32 s0, 64
	v_lshlrev_b32_e32 v3, 2, v32
	v_cndmask_b32_e32 v1, v233, v1, vcc
	v_lshlrev_b32_e32 v96, 2, v1
	v_xor_b32_e32 v1, 8, v233
	v_cmp_lt_i32_e32 vcc, v1, v0
	v_readlane_b32 s48, v254, 15
	s_cselect_b64 s[46:47], -1, 0
	v_cndmask_b32_e32 v1, v233, v1, vcc
	v_lshlrev_b32_e32 v97, 2, v1
	v_xor_b32_e32 v1, 4, v233
	v_cmp_lt_i32_e32 vcc, v1, v0
	s_add_i32 s0, 0, 0x10000
	v_readlane_b32 s49, v254, 16
	v_cndmask_b32_e32 v1, v233, v1, vcc
	v_lshlrev_b32_e32 v98, 2, v1
	v_xor_b32_e32 v1, 2, v233
	v_cmp_lt_i32_e32 vcc, v1, v0
	v_add_u32_e32 v102, s0, v3
	s_cmp_lt_i32 s16, 18
	v_cndmask_b32_e32 v1, v233, v1, vcc
	v_lshlrev_b32_e32 v99, 2, v1
	v_xor_b32_e32 v1, 1, v233
	v_cmp_lt_i32_e32 vcc, v1, v0
	s_movk_i32 s0, 0x300
	v_lshlrev_b32_e32 v4, 4, v32
	v_cndmask_b32_e32 v0, v233, v1, vcc
	v_ashrrev_i32_e32 v1, 8, v32
	v_lshlrev_b32_e32 v100, 2, v0
	v_lshlrev_b32_e32 v0, 7, v1
	s_cselect_b64 s[48:49], -1, 0
	v_cmp_gt_i32_e64 s[42:43], s0, v32
	s_add_i32 s0, 0, 0x1000
	v_lshlrev_b32_e32 v2, 12, v1
	v_and_b32_e32 v4, 0xff0, v4
	v_ashrrev_i32_e32 v7, 4, v32
	s_lshl_b32 s14, s16, 7
	s_ashr_i32 s23, s22, 31
	v_lshl_add_u32 v104, v1, 9, s0
	v_ashrrev_i32_e32 v1, 31, v0
	v_add_u32_e32 v13, 0, v3
	v_add3_u32 v101, 0, v2, v4
	v_lshlrev_b32_e32 v2, 5, v7
	s_add_i32 s15, s0, s14
	s_lshl_b64 s[22:23], s[22:23], 12
	v_readlane_b32 s17, v254, 14
	v_lshlrev_b64 v[0:1], 12, v[0:1]
	v_and_b32_e32 v3, 0xff, v32
	v_readlane_b32 s50, v254, 17
	v_readlane_b32 s51, v254, 18
	s_add_u32 s22, s17, s22
	v_readlane_b32 s17, v254, 31
	v_lshl_or_b32 v0, v3, 4, v0
	v_ashrrev_i32_e32 v3, 31, v2
	s_addc_u32 s23, s17, s23
	v_lshl_add_u64 v[86:87], s[50:51], 0, v[0:1]
	v_lshlrev_b64 v[0:1], 11, v[2:3]
	s_lshl_b32 s0, s16, 2
	v_lshlrev_b64 v[80:81], 2, v[32:33]
	v_readlane_b32 s52, v254, 19
	v_readlane_b32 s53, v254, 20
	v_readlane_b32 s56, v254, 23
	v_readlane_b32 s57, v254, 24
	v_lshl_add_u32 v94, v238, 4, 0
	v_mul_i32_i24_e32 v6, -12, v238
	v_lshl_add_u32 v8, v7, 8, 0
	v_lshlrev_b32_e32 v9, 4, v155
	v_lshlrev_b32_e32 v4, 4, v238
	v_mov_b32_e32 v5, v12
	v_lshl_or_b32 v0, v155, 4, v0
	s_add_i32 s17, s0, 0
	v_cmp_gt_i32_e64 s[38:39], 64, v32
	v_lshl_add_u64 v[82:83], s[52:53], 0, v[80:81]
	v_cmp_eq_u32_e64 s[40:41], 0, v238
	v_add_u32_e32 v103, 0x1f00, v32
	v_lshl_add_u64 v[84:85], s[22:23], 0, v[4:5]
	v_lshl_add_u64 v[88:89], s[56:57], 0, v[0:1]
	v_lshl_add_u32 v105, v7, 7, 0
	s_add_i32 s17, s17, 0x10100
	v_add_u32_e32 v106, v94, v6
	v_add_u32_e32 v107, v8, v9
	v_lshlrev_b32_e32 v108, 2, v238
	s_and_b32 s34, s78, 7
	s_lshl_b32 s34, s34, 4
	s_lshr_b32 s19, s78, 3
	s_or_b32 s34, s34, s19
	s_cmpk_lt_u32 s78, 0x80
	s_cselect_b32 s34, s34, s78
	s_cmpk_eq_u32 s10, 0x100
	s_cselect_b32 s34, s34, s78
	s_mov_b32 s19, s34
	v_readlane_b32 s54, v254, 21
	v_readlane_b32 s55, v254, 22
	v_readlane_b32 s58, v254, 25
	v_readlane_b32 s59, v254, 26
	v_readlane_b32 s60, v254, 27
	v_readlane_b32 s61, v254, 28
	v_readlane_b32 s62, v254, 29
	v_readlane_b32 s63, v254, 30
	s_branch .LBB0_96

; #define LAS __attribute__((address_space(3)))
; DI bf16_t f2bf(float f) { return (bf16_t)(cvt_pk_bf16(f, 0.f) & 0xffffu); }
; DI void gla_item(ldsp lds, const Params& p, const bf16_t* proj, bf16_t* obuf, const float* q0k0, int jl, int item, int tid, int wid, int lane) {
;     const int half = item & 1, h = (item >> 1) & 3, b = item >> 3;
;     constexpr int O_GL = 0, O_WG = 5120, O_BG = 12800, O_LA = 13312, O_QI = 38912, O_KI = 52224, O_KO = 65536, O_V = 78848, O_AM = 92160, O_ST = 101376;
;     constexpr int S96 = 208, SGL = 80, SAM = 144, SLA = 100;
;     const ldsp GL = lds + O_GL, WG = lds + O_WG, QI = lds + O_QI, KI = lds + O_KI, KO = lds + O_KO, Vl = lds + O_V, AM = lds + O_AM, ST = lds + O_ST;
;     LAS float* BG = (LAS float*)(lds + O_BG);
;     LAS float* LA = (LAS float*)(lds + O_LA);
;     const int li = lane & 15, quad = lane >> 4;
;     {
;         float wv6[6];
; #pragma unroll
;         for (int i = 0; i < 6; ++i) { const int e = tid + i * 512, d = e >> 5, kk = e & 31;
;             wv6[i] = kk < 16 ? p.w_gate_up[(size_t)(jl * 16 + kk) * 384 + h * 96 + d] : 0.f; }
; #pragma unroll
;         for (int i = 0; i < 6; ++i) { const int e = tid + i * 512, d = e >> 5, kk = e & 31; *(LAS bf16_t*)(WG + d * SGL + kk * 2) = f2bf(wv6[i]); }
;     }
;     for (int e = tid; e < 64 * 40; e += 512) *(LAS bf16_t*)(GL + e * 2) = 0;
;     if (tid < 96) BG[tid] = p.b_gate[jl * 384 + h * 96 + tid];
;     float a00;
;     {
;         const float* qp = q0k0 + b * 768 + h * 96; const float* kp = qp + 384;
;         float t = qp[lane] * kp[lane] + (lane < 32 ? qp[64 + lane] * kp[64 + lane] : 0.f);
;         a00 = wave_sum(t) * 0.10206207261596575f;
;     }
;     f32x4 S[6];
; #pragma unroll
;     for (int i = 0; i < 6; ++i) S[i] = (f32x4){0.f, 0.f, 0.f, 0.f};
;     __syncthreads();
;     const int c0 = tid, c1 = tid + 512;
;     const int row0 = c0 / 12, ch0 = c0 - row0 * 12, row1 = c1 / 12, ch1 = c1 - row1 * 12;
;     const bool has1 = tid < 256;
;     u32x4 qreg0, kreg0, vreg0, qreg1 = (u32x4){0u, 0u, 0u, 0u}, kreg1 = qreg1, vreg1 = qreg1, greg = qreg1;
.LBB0_448:
	s_and_b64 vcc, exec, s[22:23]
	s_cbranch_vccz .LBB0_652
	v_readlane_b32 s14, v251, 52
	v_readlane_b32 s15, v251, 53
	v_lshrrev_b32_e32 v145, 4, v238
	v_and_b32_e32 v69, 48, v32
	s_waitcnt vmcnt(0)
	v_or_b32_e32 v1, 48, v238
	s_mov_b32 s70, s93
	s_andn2_b64 vcc, exec, s[14:15]
	v_bfe_u32 v144, v32, 2, 2
	v_lshlrev_b32_e32 v68, 3, v145
	v_add_u32_e32 v89, 0, v69
	v_mul_u32_u24_e32 v93, 0x90, v1
	v_readlane_b32 s76, v255, 15
	s_cbranch_vccnz .LBB0_504
	v_readlane_b32 s40, v254, 15
	v_readlane_b32 s14, v254, 63
	v_and_b32_e32 v0, 31, v32
	v_readlane_b32 s54, v254, 29
	v_readlane_b32 s55, v254, 30
	v_readlane_b32 s15, v255, 0
	v_cmp_gt_u32_e64 s[38:39], 16, v0
	v_lshl_add_u32 v0, s14, 4, v0
	v_mov_b64_e32 v[2:3], s[54:55]
	s_movk_i32 s22, 0x600
	s_mul_i32 s0, s14, 0x180
	v_mad_u64_u32 v[70:71], s[14:15], v0, s22, v[2:3]
	v_add_u32_e32 v2, 0x800, v32
	v_ashrrev_i32_e32 v80, 5, v2
	v_add_u32_e32 v2, 0xa00, v32
	v_lshlrev_b32_e32 v147, 1, v32
	v_ashrrev_i32_e32 v82, 5, v2
	v_and_b32_e32 v2, 62, v147
	v_and_b32_e32 v11, 64, v233
	v_add_u32_e32 v13, 0, v2
	v_add_u32_e32 v2, 64, v11
	v_xor_b32_e32 v3, 32, v233
	v_cmp_lt_i32_e32 vcc, v3, v2
	v_add_u32_e32 v0, 0x200, v32
	v_add_u32_e32 v34, 0x400, v32
	v_cndmask_b32_e32 v3, v233, v3, vcc
	v_lshlrev_b32_e32 v150, 2, v3
	v_xor_b32_e32 v3, 16, v233
	v_cmp_lt_i32_e32 vcc, v3, v2
	v_add_u32_e32 v35, 0x600, v32
	v_add_u32_e32 v148, s0, v32
	v_cndmask_b32_e32 v3, v233, v3, vcc
	v_lshlrev_b32_e32 v151, 2, v3
	v_xor_b32_e32 v3, 8, v233
	v_cmp_lt_i32_e32 vcc, v3, v2
	s_mov_b32 s0, 0x2aaaaaab
	v_ashrrev_i32_e32 v72, 5, v32
	v_cndmask_b32_e32 v3, v233, v3, vcc
	v_lshlrev_b32_e32 v152, 2, v3
	v_xor_b32_e32 v3, 4, v233
	v_cmp_lt_i32_e32 vcc, v3, v2
	v_ashrrev_i32_e32 v74, 5, v0
	v_ashrrev_i32_e32 v76, 5, v34
	v_cndmask_b32_e32 v3, v233, v3, vcc
	v_lshlrev_b32_e32 v153, 2, v3
	v_xor_b32_e32 v3, 2, v233
	v_cmp_lt_i32_e32 vcc, v3, v2
	v_ashrrev_i32_e32 v78, 5, v35
	s_movk_i32 s14, 0x50
	v_cndmask_b32_e32 v3, v233, v3, vcc
	v_lshlrev_b32_e32 v155, 2, v3
	v_xor_b32_e32 v3, 1, v233
	v_cmp_lt_i32_e32 vcc, v3, v2
	v_readlane_b32 s41, v254, 16
	v_mul_lo_u32 v18, v72, s14
	v_cndmask_b32_e32 v2, v233, v3, vcc
	v_lshlrev_b32_e32 v156, 2, v2
	v_mul_hi_i32 v2, v32, s0
	v_mul_lo_u32 v19, v74, s14
	v_mul_lo_u32 v20, v76, s14
	v_mul_lo_u32 v21, v78, s14
	v_mul_lo_u32 v22, v80, s14
	v_mul_lo_u32 v23, v82, s14
	s_movk_i32 s14, 0xa00
	v_lshrrev_b32_e32 v3, 31, v2
	v_ashrrev_i32_e32 v2, 1, v2
	v_readlane_b32 s42, v254, 17
	v_readlane_b32 s43, v254, 18
	v_cmp_gt_i32_e64 s[40:41], s14, v32
	s_movk_i32 s14, 0x60
	v_add_u32_e32 v84, v2, v3
	v_cmp_gt_i32_e64 s[42:43], s14, v32
	v_mad_u64_u32 v[2:3], s[14:15], v84, -12, v[32:33]
	v_mul_hi_i32 v3, v0, s0
	v_readlane_b32 s46, v254, 21
	v_readlane_b32 s47, v254, 22
	v_lshrrev_b32_e32 v4, 31, v3
	v_ashrrev_i32_e32 v3, 1, v3
	s_movk_i32 s0, 0x100
	v_readlane_b32 s48, v254, 23
	v_readlane_b32 s49, v254, 24
	v_add_u32_e32 v86, v3, v4
	v_cmp_gt_i32_e64 s[46:47], s0, v32
	s_movk_i32 s0, 0x80
	s_cmp_lt_i32 s16, 6
	v_readlane_b32 s31, v255, 14
	v_mad_u64_u32 v[4:5], s[14:15], v86, -12, v[0:1]
	v_cmp_gt_i32_e64 s[48:49], s0, v32
	s_cselect_b64 s[36:37], -1, 0
	s_bfe_u32 s0, s31, 0x20006
	s_lshl_b32 s14, s0, 5
	v_readlane_b32 s19, v254, 48
	s_add_i32 s14, s19, s14
	v_and_b32_e32 v146, 15, v32
	v_add_u32_e32 v26, s14, v68
	s_lshl_b32 s14, s0, 4
	s_movk_i32 s23, 0xd0
	v_or_b32_e32 v3, s14, v146
	v_mad_u32_u24 v27, v3, s23, 0
	v_lshlrev_b32_e32 v3, 4, v32
	s_lshl_b32 s26, s16, 4
	v_and_b32_e32 v10, 16, v3
	v_or_b32_e32 v3, s26, v146
	v_add_u32_e32 v14, -16, v233
	v_lshl_or_b32 v17, v145, 2, s14
	v_lshl_add_u32 v92, v3, 2, 0
	s_movk_i32 s14, 0x4c
	v_cmp_lt_i32_e32 vcc, v14, v11
	v_mad_u64_u32 v[94:95], s[14:15], v3, s14, v[92:93]
	s_nop 0
	v_cndmask_b32_e32 v14, v14, v233, vcc
	v_lshlrev_b32_e32 v95, 2, v14
	v_subrev_u32_e32 v14, 32, v233
	v_cmp_lt_i32_e32 vcc, v14, v11
	s_movk_i32 s14, 0xffb4
	v_mul_lo_u32 v5, v84, s23
	v_cndmask_b32_e32 v14, v14, v233, vcc
	v_lshlrev_b32_e32 v163, 2, v14
	v_mad_u64_u32 v[14:15], s[14:15], v3, s14, v[94:95]
	v_mul_lo_u32 v3, v3, s23
	v_readlane_b32 s14, v254, 49
	v_readlane_b32 s17, v254, 47
	v_mul_lo_u32 v30, v86, s23
	v_add_u32_e32 v165, s14, v3
	v_lshlrev_b32_e32 v3, 2, v238
	v_and_b32_e32 v15, 12, v3
	v_or_b32_e32 v3, s26, v15
	v_add_u32_e32 v24, s17, v5
	v_add_u32_e32 v31, s17, v30
	v_lshl_add_u32 v37, v3, 1, s17
	s_movk_i32 s17, 0x190
	v_mul_lo_u32 v3, v84, s17
	v_lshlrev_b32_e32 v6, 3, v2
	v_lshlrev_b32_e32 v25, 4, v2
	v_add_u32_e32 v16, 0, v3
	v_lshlrev_b32_e32 v2, 5, v2
	s_movk_i32 s30, 0xff40
	v_add_u32_e32 v38, s19, v69
	v_add_u32_e32 v166, v16, v2
	v_add_u32_e32 v167, 0, v2
	v_mad_u64_u32 v[2:3], s[14:15], v84, s30, v[16:17]
	s_add_i32 s19, 0, 0x10000
	v_add_u32_e32 v3, s19, v5
	v_mul_lo_u32 v5, v86, s17
	v_lshlrev_b32_e32 v8, 3, v4
	v_lshlrev_b32_e32 v36, 4, v4
	v_add_u32_e32 v16, 0, v5
	v_lshlrev_b32_e32 v4, 5, v4
	v_add_u32_e32 v168, v16, v4
	v_add_u32_e32 v169, 0, v4
	v_mad_u64_u32 v[4:5], s[14:15], v86, s30, v[16:17]
	s_ashr_i32 s27, s26, 31
	s_ashr_i32 s14, s31, 8
	s_cmp_le_i32 s0, s14
	s_cselect_b64 s[30:31], -1, 0
	s_add_i32 s17, s16, 8
	v_or_b32_e32 v11, v11, v1
	v_mul_u32_u24_e32 v41, 0x50, v1
	v_add_u32_e32 v5, s19, v30
	v_lshl_or_b32 v30, s14, 4, v146
	s_ashr_i32 s14, s17, 2
	s_waitcnt lgkmcnt(0)
; DI void gla_item(ldsp lds, const Params& p, const bf16_t* proj, bf16_t* obuf, const float* q0k0, int jl, int item, int tid, int wid, int lane) {
;     ...
;     const int c0 = tid, c1 = tid + 512;
;     const int row0 = c0 / 12, ch0 = c0 - row0 * 12, row1 = c1 / 12, ch1 = c1 - row1 * 12;
;     const bool has1 = tid < 256;
;     u32x4 qreg0, kreg0, vreg0, qreg1 = (u32x4){0u, 0u, 0u, 0u}, kreg1 = qreg1, vreg1 = qreg1, greg = qreg1;
;     ...
;     GLA_LOAD_CHUNK(0);
;     for (int n = 0; n < 32; ++n) {
; __global__ void __launch_bounds__(NTHREADS, 2) megak(Params p) {
;     ...
;                 for (int it = blockIdx.x; it < BATCH * 8; it += gridDim.x) gla_item(lds, p, PROJ, OBUF, Q0K0, jl, it, tid, wid, lane);
	v_mul_u32_u24_e32 v45, 0xd0, v1
	v_max_i32_e32 v1, 0x800, v32
	v_mul_lo_u32 v16, v30, s23
	s_cmp_le_i32 s0, s14
	v_lshl_or_b32 v33, s14, 4, v146
	v_sub_u32_e32 v1, v1, v32
	v_add_u32_e32 v42, 0, v16
	s_cselect_b64 s[72:73], -1, 0
	v_mul_lo_u32 v16, v33, s23
	s_lshl_b64 s[14:15], s[26:27], 1
	v_add_u32_e32 v47, 0x1ff, v1
	v_ashrrev_i32_e32 v9, 31, v8
	v_or_b32_e32 v28, 2, v17
	v_or_b32_e32 v29, 3, v17
	v_lshlrev_b32_e32 v164, 2, v11
	v_or_b32_e32 v11, v68, v144
	v_cmp_gt_i32_e64 s[54:55], v17, v30
	v_cmp_lt_i32_e64 s[56:57], v17, v30
	v_add_u32_e32 v43, 0, v16
	v_cmp_gt_i32_e64 s[62:63], v17, v33
	v_cmp_lt_i32_e64 s[64:65], v17, v33
	v_mov_b64_e32 v[16:17], s[14:15]
	s_movk_i32 s0, 0x90
	v_lshrrev_b32_e32 v1, 9, v47
	v_readlane_b32 s14, v251, 15
	v_cmp_gt_i32_e64 s[58:59], v28, v30
	v_cmp_gt_i32_e64 s[66:67], v28, v33
	v_cmp_gt_i32_e64 s[68:69], v29, v33
	v_mul_u32_u24_e32 v28, 0xd0, v11
	v_mul_lo_u32 v46, v33, s0
	v_add_u32_e32 v48, 1, v1
	v_mov_b32_e32 v33, v0
	v_mov_b32_e32 v11, v12
	v_readlane_b32 s15, v251, 16
	v_lshlrev_b64 v[98:99], 1, v[8:9]
	v_mov_b64_e32 v[0:1], 0x68a0600
	s_waitcnt lgkmcnt(0)
	v_ashrrev_i32_e32 v7, 31, v6
	v_lshl_add_u64 v[96:97], s[14:15], 0, v[10:11]
	v_mad_i64_i32 v[100:101], s[14:15], v86, s94, v[0:1]
	v_mad_i64_i32 v[104:105], s[14:15], v86, s94, v[98:99]
	v_and_b32_e32 v0, 1, v32
	v_mov_b32_e32 v1, 0x68a0c00
	v_lshl_or_b32 v106, v0, 4, v1
	v_lshlrev_b64 v[108:109], 1, v[6:7]
	s_mov_b64 s[14:15], 0x68a0600
	v_mov_b64_e32 v[0:1], s[6:7]
	v_lshl_add_u64 v[110:111], v[108:109], 0, s[14:15]
	v_mad_i64_i32 v[112:113], s[14:15], v84, s94, v[0:1]
	v_mul_u32_u24_e32 v6, 0x600, v146
	v_lshrrev_b32_e32 v0, 1, v69
	v_mad_i64_i32 v[114:115], s[14:15], v84, s94, v[108:109]
	v_or_b32_e32 v116, v6, v0
	v_mad_u64_u32 v[6:7], s[14:15], v146, s22, v[16:17]
	v_cmp_gt_i32_e64 s[60:61], v29, v30
	v_mul_lo_u32 v30, v30, s0
	s_mov_b64 s[14:15], 0x26840000
	s_movk_i32 s0, 0x5ff
	v_lshl_add_u64 v[118:119], v[6:7], 0, s[14:15]
	v_cmp_lt_u32_e64 s[14:15], s0, v47
	v_and_b32_e32 v170, 0xfffffc, v48
	v_readlane_b32 s44, v254, 19
	v_writelane_b32 v255, s14, 17
	v_readlane_b32 s45, v254, 20
	v_readlane_b32 s50, v254, 25
	v_writelane_b32 v255, s15, 18
	v_cmp_ne_u32_e64 s[14:15], v48, v170
	v_readlane_b32 s51, v254, 26
	v_readlane_b32 s52, v254, 27
	v_readlane_b32 s53, v254, 28
	v_ashrrev_i32_e32 v90, 1, v32
	v_mul_u32_u24_e32 v39, 0x50, v146
	v_mul_u32_u24_e32 v40, 0x640, v145
	v_lshl_add_u32 v15, v15, 1, s19
	v_mul_u32_u24_e32 v29, 0x90, v146
	v_mul_u32_u24_e32 v44, 0xd0, v146
	v_mov_b32_e32 v1, v12
	v_writelane_b32 v255, s14, 19
	v_ashrrev_i32_e32 v73, 31, v72
	v_ashrrev_i32_e32 v75, 31, v74
	v_ashrrev_i32_e32 v77, 31, v76
	v_ashrrev_i32_e32 v79, 31, v78
	v_ashrrev_i32_e32 v81, 31, v80
	v_ashrrev_i32_e32 v83, 31, v82
	s_movk_i32 s71, 0x50
	v_lshl_add_u32 v149, v32, 2, 0
	v_cmp_gt_u32_e64 s[44:45], 32, v238
	v_ashrrev_i32_e32 v85, 31, v84
	v_ashrrev_i32_e32 v87, 31, v86
	v_lshrrev_b32_e32 v88, 1, v32
	v_ashrrev_i32_e32 v91, 31, v90
	v_cmp_gt_u32_e64 s[50:51], 16, v238
	v_add_u32_e32 v162, 0, v10
	v_cmp_lt_u32_e64 s[52:53], 31, v238
	v_lshl_add_u32 v171, v170, 9, v32
	v_lshl_add_u64 v[102:103], s[6:7], 0, v[98:99]
	v_mov_b32_e32 v107, v12
	v_mul_hi_u32_u24_e32 v117, 0x600, v146
	v_lshl_add_u64 v[120:121], s[6:7], 0, v[0:1]
	v_add_u32_e32 v172, v13, v18
	v_add_u32_e32 v173, v13, v19
	v_add_u32_e32 v174, v13, v20
	v_add_u32_e32 v175, v13, v21
	v_add_u32_e32 v176, v13, v22
	v_add_u32_e32 v177, v13, v23
	v_lshlrev_b32_e32 v122, 2, v238
	v_add_u32_e32 v178, v24, v25
	v_add_u32_e32 v179, v31, v36
	v_add_u32_e32 v180, v89, v39
	v_add_u32_e32 v181, v14, v40
	v_add_u32_e32 v182, v89, v41
	v_add_u32_e32 v183, v2, v25
	v_add_u32_e32 v184, v3, v25
	v_add_u32_e32 v185, v4, v36
	v_add_u32_e32 v186, v5, v36
	v_add_u32_e32 v187, v42, v69
	v_add_u32_e32 v188, v26, v30
	v_add_u32_e32 v189, v43, v69
	v_add_u32_e32 v190, v26, v46
	v_add_u32_e32 v191, v37, v28
	v_add_u32_e32 v192, v38, v29
	v_add_u32_e32 v193, v38, v93
	v_add_u32_e32 v194, v89, v44
	v_add_u32_e32 v195, v89, v45
	v_add_u32_e32 v196, v15, v28
	v_add_u32_e32 v197, v27, v69
	v_readlane_b32 s19, v254, 54
	v_writelane_b32 v255, s15, 20
	s_and_b32 s98, s19, 7
	s_lshl_b32 s98, s98, 5
	s_lshr_b32 s99, s19, 3
	s_or_b32 s98, s98, s99
	s_cmpk_eq_u32 s10, 0x100
	s_cselect_b32 s19, s98, s19
	s_branch .LBB0_452

; #define LAS __attribute__((address_space(3)))
; DI float silu_f(float x) { return x / (1.0f + __expf(-x)); }
; DI void tok0_mix_gla(ldsp lds, const Params& p, const float* P, float* BRo, int task, int tid, int wid, int lane) {
;     const int b = task >> 2, hm = task & 3;
;     const float* pr = P + (size_t)b * 8192;
;     LAS float* OUT = (LAS float*)(lds + 65536); LAS float* R3 = OUT + 64;
;     tok0_mem(lds, pr + GA_QM + hm * 64, p.mem + (size_t)b * 256 * 1024, p.mem_norm_w, p.w_memkv, hm, OUT, tid, wid, lane);
;     if (tid < 64) BRo[(size_t)b * 1024 + 768 + hm * 64 + tid] = OUT[tid] * silu_f(pr[GA_GATE + 768 + hm * 64 + tid]);
;     const float* qp = pr + hm * 96; const float* kp = pr + GA_K + hm * 96;
;     const float a = wave_sum(qp[lane] * kp[lane] + (lane < 32 ? qp[64 + lane] * kp[64 + lane] : 0.f)) * 0.10206207261596575f;
;     float ve = 0.f;
;     if (tid < 192) ve = pr[GA_V + hm * 192 + tid];
;     const float sq = wave_sum(ve * ve);
;     if (lane == 0 && wid < 3) R3[wid] = sq;
;     __syncthreads();
;     const float msv = (R3[0] + R3[1] + R3[2]) * (1.0f / 192.0f);
;     const float rs = rsqrtf(a * a * msv + 1e-6f);
;     if (tid < 192) BRo[(size_t)b * 1024 + hm * 192 + tid] = a * ve * rs * p.gla_norm_w[tid] * silu_f(pr[GA_GATE + hm * 192 + tid]);
; __global__ void __launch_bounds__(NTHREADS, 2) megak(Params p) {
;     ...
;                 if (L == 0) for (int t = blockIdx.x; t < BATCH * 4; t += gridDim.x) tok0_mix_gla(lds, p, T0P, T0BR, t, tid, wid, lane);
.LBB0_827:
	v_readlane_b32 s14, v251, 43
	v_readlane_b32 s18, v255, 7
	v_readlane_b32 s15, v251, 44
	v_readlane_b32 s19, v255, 8
	s_or_b64 s[14:15], s[18:19], s[14:15]
	s_and_b64 vcc, exec, s[14:15]
	s_cbranch_vccnz .LBB0_860
	v_and_b32_e32 v2, 64, v233
	v_add_u32_e32 v2, 64, v2
	v_xor_b32_e32 v4, 32, v233
	v_cmp_lt_i32_e32 vcc, v4, v2
	s_lshl_b32 s22, s16, 5
	v_readlane_b32 s0, v255, 14
	v_cndmask_b32_e32 v4, v233, v4, vcc
	v_lshlrev_b32_e32 v97, 2, v4
	v_xor_b32_e32 v4, 16, v233
	v_cmp_lt_i32_e32 vcc, v4, v2
	v_lshlrev_b64 v[0:1], 11, v[32:33]
	s_mov_b64 s[14:15], 0x100000
	v_cndmask_b32_e32 v4, v233, v4, vcc
	v_lshlrev_b32_e32 v98, 2, v4
	v_xor_b32_e32 v4, 8, v233
	v_cmp_lt_i32_e32 vcc, v4, v2
	s_cmp_lt_u32 s0, 64
	v_lshlrev_b32_e32 v3, 2, v32
	v_cndmask_b32_e32 v4, v233, v4, vcc
	v_lshlrev_b32_e32 v99, 2, v4
	v_xor_b32_e32 v4, 4, v233
	v_cmp_lt_i32_e32 vcc, v4, v2
	v_lshl_add_u64 v[78:79], v[0:1], 0, s[14:15]
	v_readlane_b32 s44, v254, 15
	v_cndmask_b32_e32 v4, v233, v4, vcc
	v_lshlrev_b32_e32 v100, 2, v4
	v_xor_b32_e32 v4, 2, v233
	v_cmp_lt_i32_e32 vcc, v4, v2
	s_cselect_b64 s[14:15], -1, 0
	s_add_i32 s0, 0, 0x10000
	v_readlane_b32 s45, v254, 16
	v_cndmask_b32_e32 v4, v233, v4, vcc
	v_add_u32_e32 v104, s0, v3
	s_movk_i32 s0, 0xc0
	s_cmp_lt_i32 s16, 3
	v_lshlrev_b32_e32 v101, 2, v4
	v_xor_b32_e32 v4, 1, v233
	v_cmp_gt_i32_e64 s[44:45], s0, v32
	s_cselect_b64 s[18:19], -1, 0
	s_lshl_b32 s0, s16, 2
	v_readlane_b32 s56, v254, 27
	v_readlane_b32 s57, v254, 28
	v_readlane_b32 s58, v254, 29
	v_readlane_b32 s59, v254, 30
	v_cmp_lt_i32_e32 vcc, v4, v2
	v_cmp_eq_u32_e64 s[40:41], 0, v238
	s_add_i32 s17, s0, 0
	s_lshl_b32 s0, s16, 7
	s_add_i32 s26, 0, 0x1000
	s_ashr_i32 s23, s22, 31
	v_cndmask_b32_e32 v2, v233, v4, vcc
	v_ashrrev_i32_e32 v5, 8, v32
	v_lshlrev_b32_e32 v7, 4, v32
	s_and_b64 s[18:19], s[40:41], s[18:19]
	s_add_i32 s17, s17, 0x10100
	v_readlane_b32 s56, v251, 0
	s_add_i32 s34, s26, s0
	s_lshl_b64 s[22:23], s[22:23], 12
	v_readlane_b32 s0, v254, 14
	v_lshlrev_b64 v[0:1], 2, v[32:33]
	v_readlane_b32 s48, v254, 19
	v_readlane_b32 s49, v254, 20
	v_lshlrev_b32_e32 v102, 2, v2
	v_lshlrev_b32_e32 v2, 7, v5
	v_lshlrev_b32_e32 v4, 12, v5
	v_and_b32_e32 v7, 0xff0, v7
	v_readlane_b32 s58, v251, 2
	v_readlane_b32 s59, v251, 3
	s_add_u32 s22, s0, s22
	v_readlane_b32 s0, v254, 31
	v_add_u32_e32 v13, 0, v3
	v_lshl_add_u64 v[80:81], s[48:49], 0, v[0:1]
	v_add3_u32 v103, 0, v4, v7
	v_ashrrev_i32_e32 v7, 4, v32
	v_lshl_add_u64 v[82:83], s[58:59], 0, v[0:1]
	v_lshlrev_b32_e32 v0, 4, v238
	v_mov_b32_e32 v1, v12
	s_addc_u32 s23, s0, s23
	v_ashrrev_i32_e32 v3, 31, v2
	v_lshlrev_b32_e32 v4, 5, v7
	v_lshl_add_u64 v[84:85], s[22:23], 0, v[0:1]
	v_lshlrev_b64 v[0:1], 12, v[2:3]
	v_and_b32_e32 v2, 0xff, v32
	v_readlane_b32 s46, v254, 17
	v_readlane_b32 s47, v254, 18
	v_lshl_add_u32 v107, v5, 9, s26
	v_lshl_or_b32 v0, v2, 4, v0
	v_ashrrev_i32_e32 v5, 31, v4
	v_lshl_add_u64 v[86:87], s[46:47], 0, v[0:1]
	v_lshlrev_b64 v[0:1], 11, v[4:5]
	v_readlane_b32 s52, v254, 23
	v_readlane_b32 s53, v254, 24
	v_lshl_add_u32 v96, v238, 4, 0
	v_mul_i32_i24_e32 v6, -12, v238
	v_lshl_add_u32 v8, v7, 8, 0
	v_lshlrev_b32_e32 v9, 4, v155
	v_lshl_or_b32 v0, v155, 4, v0
	v_cmp_gt_i32_e64 s[38:39], 64, v32
	v_mov_b32_e32 v30, v32
	v_mov_b32_e32 v31, v12
	v_add_u32_e32 v105, 0xa10, v32
	v_cmp_gt_u32_e64 s[42:43], 32, v238
	v_add_u32_e32 v106, 0x710, v32
	v_lshl_add_u64 v[88:89], s[52:53], 0, v[0:1]
	v_lshl_add_u32 v108, v7, 7, 0
	v_add_u32_e32 v109, v96, v6
	v_add_u32_e32 v110, v8, v9
	v_lshlrev_b32_e32 v90, 2, v238
	s_and_b32 s36, s78, 7
	s_lshl_b32 s36, s36, 4
	s_lshr_b32 s35, s78, 3
	s_or_b32 s36, s36, s35
	s_cmpk_lt_u32 s78, 0x80
	s_cselect_b32 s36, s36, s78
	s_cmpk_eq_u32 s10, 0x100
	s_cselect_b32 s36, s36, s78
	s_mov_b32 s35, s36
	v_readlane_b32 s50, v254, 21
	v_readlane_b32 s51, v254, 22
	v_readlane_b32 s54, v254, 25
	v_readlane_b32 s55, v254, 26
	v_readlane_b32 s57, v251, 1
	v_readlane_b32 s60, v251, 4
	v_readlane_b32 s61, v251, 5
	v_readlane_b32 s62, v251, 6
	v_readlane_b32 s63, v251, 7
	s_branch .LBB0_830
